# pool token mixer rewritten by hand: one wave = 64 tokens x 16 channel chunks of one window group, all 31 row loads issued up front and kept in registers (no re-load of the leaving row, no per-row vmcn
# speedup vs baseline: 1.0112x; 1.0112x over previous
; DI float bflo(unsigned v) { return __uint_as_float(v << 16); }
; DI float bfhi(unsigned v) { return __uint_as_float(v & 0xffff0000u); }
; DI void mix_pool(WVP const u16* __restrict__ proj, u16* __restrict__ pb) {
;     ...
;   for (int idx = BID * NTHR + tid; idx < (TOK / 16) * 64; idx += GRD * NTHR) {
;     const int cc = idx & 63, t0 = (idx >> 6) * 16, gi = cc >> 4, w = 2 << gi, s0 = t0 & (SEQ - 1);
;     const u16* base = proj + (long)t0 * INW + cc * 8;
;     float a[8] = {0, 0, 0, 0, 0, 0, 0, 0};
;     for (int i = 1; i < w; ++i) {
;       if (s0 - i >= 0) {
;         const u32x4 v = *(const u32x4*)(base - (long)i * INW);
;         a[0] += bflo(v[0]); a[1] += bfhi(v[0]); a[2] += bflo(v[1]); a[3] += bfhi(v[1]); a[4] += bflo(v[2]); a[5] += bfhi(v[2]); a[6] += bflo(v[3]); a[7] += bfhi(v[3]);
;       }
;     }
; #pragma unroll 4
;     for (int k = 0; k < 16; ++k) {
;       const int s = s0 + k;
;       const u32x4 v = *(const u32x4*)(base + (long)k * INW);
.LBB0_351:
	s_mov_b64 exec, -1
	v_mbcnt_lo_u32_b32 v0, -1, 0
	v_mbcnt_hi_u32_b32 v0, -1, v0
	s_lshl_b32 s0, s57, 3
	s_lshr_b32 s1, s3, 6
	s_add_i32 s0, s0, s1
	s_cmpk_gt_u32 s0, 0x7ff
	s_cbranch_scc1 .Lmp_done
.Lmp_item:
	s_and_b32 s1, s0, 3
	s_lshr_b32 s4, s0, 2
	s_lshl_b32 s11, s4, 6
	s_lshl_b32 s4, 2, s1
	s_add_i32 s5, s4, -1
	s_sub_u32 s10, 0x7e, s1
	s_lshl_b32 s10, s10, 23
	v_lshrrev_b32_e32 v2, 4, v0
	v_and_b32_e32 v3, 15, v0
	v_lshl_add_u32 v4, v2, 4, s11
	v_and_b32_e32 v5, 0xfff, v4
	v_cmp_eq_u32_e64 s[12:13], 0, v5
	s_movk_i32 s11, 0x2600
	v_mul_lo_u32 v6, v4, s11
	s_lshl_b32 s11, s1, 8
	v_lshl_add_u32 v6, v3, 4, v6
	v_add_u32_e32 v6, s11, v6
	v_lshlrev_b32_e32 v7, 10, v4
	v_lshl_add_u32 v7, v3, 4, v7
	v_add_u32_e32 v7, s11, v7
	v_mov_b32_e32 v4, s10
	s_not_b64 s[14:15], s[12:13]
	s_mul_i32 s11, s5, 0x2600
	s_sub_u32 s18, s54, s11
	s_subb_u32 s19, s55, 0
	s_cmp_lt_u32 0, s5
	s_cselect_b64 exec, s[14:15], -1
	global_load_dwordx4 v[32:35], v6, s[18:19]
	s_add_u32 s18, s18, 0x2600
	s_addc_u32 s19, s19, 0
	s_cmp_lt_u32 1, s5
	s_cselect_b64 exec, s[14:15], -1
	global_load_dwordx4 v[36:39], v6, s[18:19]
	s_add_u32 s18, s18, 0x2600
	s_addc_u32 s19, s19, 0
	s_cmp_lt_u32 2, s5
	s_cselect_b64 exec, s[14:15], -1
	global_load_dwordx4 v[40:43], v6, s[18:19]
	s_add_u32 s18, s18, 0x2600
	s_addc_u32 s19, s19, 0
	s_cmp_lt_u32 3, s5
	s_cselect_b64 exec, s[14:15], -1
	global_load_dwordx4 v[44:47], v6, s[18:19]
	s_add_u32 s18, s18, 0x2600
	s_addc_u32 s19, s19, 0
	s_cmp_lt_u32 4, s5
	s_cselect_b64 exec, s[14:15], -1
	global_load_dwordx4 v[48:51], v6, s[18:19]
	s_add_u32 s18, s18, 0x2600
	s_addc_u32 s19, s19, 0
	s_cmp_lt_u32 5, s5
	s_cselect_b64 exec, s[14:15], -1
	global_load_dwordx4 v[52:55], v6, s[18:19]
	s_add_u32 s18, s18, 0x2600
	s_addc_u32 s19, s19, 0
	s_cmp_lt_u32 6, s5
	s_cselect_b64 exec, s[14:15], -1
	global_load_dwordx4 v[56:59], v6, s[18:19]
	s_add_u32 s18, s18, 0x2600
	s_addc_u32 s19, s19, 0
	s_cmp_lt_u32 7, s5
	s_cselect_b64 exec, s[14:15], -1
	global_load_dwordx4 v[60:63], v6, s[18:19]
	s_add_u32 s18, s18, 0x2600
	s_addc_u32 s19, s19, 0
	s_cmp_lt_u32 8, s5
	s_cselect_b64 exec, s[14:15], -1
	global_load_dwordx4 v[64:67], v6, s[18:19]
	s_add_u32 s18, s18, 0x2600
	s_addc_u32 s19, s19, 0
	s_cmp_lt_u32 9, s5
	s_cselect_b64 exec, s[14:15], -1
	global_load_dwordx4 v[68:71], v6, s[18:19]
	s_add_u32 s18, s18, 0x2600
	s_addc_u32 s19, s19, 0
	s_cmp_lt_u32 10, s5
	s_cselect_b64 exec, s[14:15], -1
	global_load_dwordx4 v[72:75], v6, s[18:19]
	s_add_u32 s18, s18, 0x2600
	s_addc_u32 s19, s19, 0
	s_cmp_lt_u32 11, s5
	s_cselect_b64 exec, s[14:15], -1
	global_load_dwordx4 v[76:79], v6, s[18:19]
	s_add_u32 s18, s18, 0x2600
	s_addc_u32 s19, s19, 0
	s_cmp_lt_u32 12, s5
	s_cselect_b64 exec, s[14:15], -1
	global_load_dwordx4 v[80:83], v6, s[18:19]
	s_add_u32 s18, s18, 0x2600
	s_addc_u32 s19, s19, 0
	s_cmp_lt_u32 13, s5
	s_cselect_b64 exec, s[14:15], -1
	global_load_dwordx4 v[84:87], v6, s[18:19]
	s_add_u32 s18, s18, 0x2600
	s_addc_u32 s19, s19, 0
	s_cmp_lt_u32 14, s5
	s_cselect_b64 exec, s[14:15], -1
	global_load_dwordx4 v[88:91], v6, s[18:19]
	s_add_u32 s18, s18, 0x2600
	s_addc_u32 s19, s19, 0
	s_mov_b64 exec, -1
	s_mov_b64 s[20:21], s[54:55]
	global_load_dwordx4 v[92:95], v6, s[20:21]
	s_add_u32 s20, s20, 0x2600
	s_addc_u32 s21, s21, 0
	global_load_dwordx4 v[96:99], v6, s[20:21]
	s_add_u32 s20, s20, 0x2600
	s_addc_u32 s21, s21, 0
	global_load_dwordx4 v[100:103], v6, s[20:21]
	s_add_u32 s20, s20, 0x2600
	s_addc_u32 s21, s21, 0
	global_load_dwordx4 v[104:107], v6, s[20:21]
	s_add_u32 s20, s20, 0x2600
	s_addc_u32 s21, s21, 0
	global_load_dwordx4 v[108:111], v6, s[20:21]
	s_add_u32 s20, s20, 0x2600
	s_addc_u32 s21, s21, 0
	global_load_dwordx4 v[112:115], v6, s[20:21]
	s_add_u32 s20, s20, 0x2600
	s_addc_u32 s21, s21, 0
	global_load_dwordx4 v[116:119], v6, s[20:21]
	s_add_u32 s20, s20, 0x2600
	s_addc_u32 s21, s21, 0
	global_load_dwordx4 v[120:123], v6, s[20:21]
	s_add_u32 s20, s20, 0x2600
	s_addc_u32 s21, s21, 0
	global_load_dwordx4 v[124:127], v6, s[20:21]
	s_add_u32 s20, s20, 0x2600
	s_addc_u32 s21, s21, 0
	global_load_dwordx4 v[128:131], v6, s[20:21]
	s_add_u32 s20, s20, 0x2600
	s_addc_u32 s21, s21, 0
	global_load_dwordx4 v[132:135], v6, s[20:21]
	s_add_u32 s20, s20, 0x2600
	s_addc_u32 s21, s21, 0
	global_load_dwordx4 v[136:139], v6, s[20:21]
	s_add_u32 s20, s20, 0x2600
	s_addc_u32 s21, s21, 0
	global_load_dwordx4 v[140:143], v6, s[20:21]
	s_add_u32 s20, s20, 0x2600
	s_addc_u32 s21, s21, 0
	global_load_dwordx4 v[144:147], v6, s[20:21]
	s_add_u32 s20, s20, 0x2600
	s_addc_u32 s21, s21, 0
	global_load_dwordx4 v[148:151], v6, s[20:21]
	s_add_u32 s20, s20, 0x2600
	s_addc_u32 s21, s21, 0
	global_load_dwordx4 v[152:155], v6, s[20:21]
	s_add_u32 s18, s54, 0x17000000
	s_addc_u32 s19, s55, 0
	v_mov_b32_e32 v16, 0
	v_mov_b32_e32 v17, 0
	v_mov_b32_e32 v18, 0
	v_mov_b32_e32 v19, 0
	v_mov_b32_e32 v20, 0
	v_mov_b32_e32 v21, 0
	v_mov_b32_e32 v22, 0
	v_mov_b32_e32 v23, 0
	s_waitcnt vmcnt(16)
	s_cmp_eq_u32 s1, 3
	s_cbranch_scc1 .Lmp_w14
	s_cmp_eq_u32 s1, 2
	s_cbranch_scc1 .Lmp_w6
	s_cmp_eq_u32 s1, 1
	s_cbranch_scc1 .Lmp_w2
	s_branch .Lmp_w0
; DI float bflo(unsigned v) { return __uint_as_float(v << 16); }
; DI float bfhi(unsigned v) { return __uint_as_float(v & 0xffff0000u); }
; DI void mix_pool(WVP const u16* __restrict__ proj, u16* __restrict__ pb) {
;     ...
;     for (int i = 1; i < w; ++i) {
;       if (s0 - i >= 0) {
;         const u32x4 v = *(const u32x4*)(base - (long)i * INW);
;         a[0] += bflo(v[0]); a[1] += bfhi(v[0]); a[2] += bflo(v[1]); a[3] += bfhi(v[1]); a[4] += bflo(v[2]); a[5] += bfhi(v[2]); a[6] += bflo(v[3]); a[7] += bfhi(v[3]);
;       }
;     }
.Lmp_w14:
	s_mov_b64 exec, s[12:13]
	v_mov_b32_e32 v88, 0
	v_mov_b32_e32 v89, 0
	v_mov_b32_e32 v90, 0
	v_mov_b32_e32 v91, 0
	s_mov_b64 exec, -1
	v_lshlrev_b32_e32 v24, 16, v88
	v_and_b32_e32 v25, 0xffff0000, v88
	v_lshlrev_b32_e32 v26, 16, v89
	v_and_b32_e32 v27, 0xffff0000, v89
	v_lshlrev_b32_e32 v28, 16, v90
	v_and_b32_e32 v29, 0xffff0000, v90
	v_lshlrev_b32_e32 v30, 16, v91
	v_and_b32_e32 v31, 0xffff0000, v91
	v_pk_add_f32 v[16:17], v[16:17], v[24:25]
	v_pk_add_f32 v[18:19], v[18:19], v[26:27]
	v_pk_add_f32 v[20:21], v[20:21], v[28:29]
	v_pk_add_f32 v[22:23], v[22:23], v[30:31]
	s_mov_b64 exec, s[12:13]
	v_mov_b32_e32 v84, 0
	v_mov_b32_e32 v85, 0
	v_mov_b32_e32 v86, 0
	v_mov_b32_e32 v87, 0
	s_mov_b64 exec, -1
	v_lshlrev_b32_e32 v24, 16, v84
	v_and_b32_e32 v25, 0xffff0000, v84
	v_lshlrev_b32_e32 v26, 16, v85
	v_and_b32_e32 v27, 0xffff0000, v85
	v_lshlrev_b32_e32 v28, 16, v86
	v_and_b32_e32 v29, 0xffff0000, v86
	v_lshlrev_b32_e32 v30, 16, v87
	v_and_b32_e32 v31, 0xffff0000, v87
	v_pk_add_f32 v[16:17], v[16:17], v[24:25]
	v_pk_add_f32 v[18:19], v[18:19], v[26:27]
	v_pk_add_f32 v[20:21], v[20:21], v[28:29]
	v_pk_add_f32 v[22:23], v[22:23], v[30:31]
	s_mov_b64 exec, s[12:13]
	v_mov_b32_e32 v80, 0
	v_mov_b32_e32 v81, 0
	v_mov_b32_e32 v82, 0
	v_mov_b32_e32 v83, 0
	s_mov_b64 exec, -1
	v_lshlrev_b32_e32 v24, 16, v80
	v_and_b32_e32 v25, 0xffff0000, v80
	v_lshlrev_b32_e32 v26, 16, v81
	v_and_b32_e32 v27, 0xffff0000, v81
	v_lshlrev_b32_e32 v28, 16, v82
	v_and_b32_e32 v29, 0xffff0000, v82
	v_lshlrev_b32_e32 v30, 16, v83
	v_and_b32_e32 v31, 0xffff0000, v83
	v_pk_add_f32 v[16:17], v[16:17], v[24:25]
	v_pk_add_f32 v[18:19], v[18:19], v[26:27]
	v_pk_add_f32 v[20:21], v[20:21], v[28:29]
	v_pk_add_f32 v[22:23], v[22:23], v[30:31]
	s_mov_b64 exec, s[12:13]
	v_mov_b32_e32 v76, 0
	v_mov_b32_e32 v77, 0
	v_mov_b32_e32 v78, 0
	v_mov_b32_e32 v79, 0
	s_mov_b64 exec, -1
	v_lshlrev_b32_e32 v24, 16, v76
	v_and_b32_e32 v25, 0xffff0000, v76
	v_lshlrev_b32_e32 v26, 16, v77
	v_and_b32_e32 v27, 0xffff0000, v77
	v_lshlrev_b32_e32 v28, 16, v78
	v_and_b32_e32 v29, 0xffff0000, v78
	v_lshlrev_b32_e32 v30, 16, v79
	v_and_b32_e32 v31, 0xffff0000, v79
	v_pk_add_f32 v[16:17], v[16:17], v[24:25]
	v_pk_add_f32 v[18:19], v[18:19], v[26:27]
	v_pk_add_f32 v[20:21], v[20:21], v[28:29]
	v_pk_add_f32 v[22:23], v[22:23], v[30:31]
	s_mov_b64 exec, s[12:13]
	v_mov_b32_e32 v72, 0
	v_mov_b32_e32 v73, 0
	v_mov_b32_e32 v74, 0
	v_mov_b32_e32 v75, 0
	s_mov_b64 exec, -1
	v_lshlrev_b32_e32 v24, 16, v72
	v_and_b32_e32 v25, 0xffff0000, v72
	v_lshlrev_b32_e32 v26, 16, v73
	v_and_b32_e32 v27, 0xffff0000, v73
	v_lshlrev_b32_e32 v28, 16, v74
	v_and_b32_e32 v29, 0xffff0000, v74
	v_lshlrev_b32_e32 v30, 16, v75
	v_and_b32_e32 v31, 0xffff0000, v75
	v_pk_add_f32 v[16:17], v[16:17], v[24:25]
	v_pk_add_f32 v[18:19], v[18:19], v[26:27]
	v_pk_add_f32 v[20:21], v[20:21], v[28:29]
	v_pk_add_f32 v[22:23], v[22:23], v[30:31]
	s_mov_b64 exec, s[12:13]
	v_mov_b32_e32 v68, 0
	v_mov_b32_e32 v69, 0
	v_mov_b32_e32 v70, 0
	v_mov_b32_e32 v71, 0
	s_mov_b64 exec, -1
	v_lshlrev_b32_e32 v24, 16, v68
	v_and_b32_e32 v25, 0xffff0000, v68
	v_lshlrev_b32_e32 v26, 16, v69
	v_and_b32_e32 v27, 0xffff0000, v69
	v_lshlrev_b32_e32 v28, 16, v70
	v_and_b32_e32 v29, 0xffff0000, v70
	v_lshlrev_b32_e32 v30, 16, v71
	v_and_b32_e32 v31, 0xffff0000, v71
	v_pk_add_f32 v[16:17], v[16:17], v[24:25]
	v_pk_add_f32 v[18:19], v[18:19], v[26:27]
	v_pk_add_f32 v[20:21], v[20:21], v[28:29]
	v_pk_add_f32 v[22:23], v[22:23], v[30:31]
	s_mov_b64 exec, s[12:13]
	v_mov_b32_e32 v64, 0
	v_mov_b32_e32 v65, 0
	v_mov_b32_e32 v66, 0
	v_mov_b32_e32 v67, 0
	s_mov_b64 exec, -1
	v_lshlrev_b32_e32 v24, 16, v64
	v_and_b32_e32 v25, 0xffff0000, v64
	v_lshlrev_b32_e32 v26, 16, v65
	v_and_b32_e32 v27, 0xffff0000, v65
	v_lshlrev_b32_e32 v28, 16, v66
	v_and_b32_e32 v29, 0xffff0000, v66
	v_lshlrev_b32_e32 v30, 16, v67
	v_and_b32_e32 v31, 0xffff0000, v67
	v_pk_add_f32 v[16:17], v[16:17], v[24:25]
	v_pk_add_f32 v[18:19], v[18:19], v[26:27]
	v_pk_add_f32 v[20:21], v[20:21], v[28:29]
	v_pk_add_f32 v[22:23], v[22:23], v[30:31]
	s_mov_b64 exec, s[12:13]
	v_mov_b32_e32 v60, 0
	v_mov_b32_e32 v61, 0
	v_mov_b32_e32 v62, 0
	v_mov_b32_e32 v63, 0
	s_mov_b64 exec, -1
	v_lshlrev_b32_e32 v24, 16, v60
	v_and_b32_e32 v25, 0xffff0000, v60
	v_lshlrev_b32_e32 v26, 16, v61
	v_and_b32_e32 v27, 0xffff0000, v61
	v_lshlrev_b32_e32 v28, 16, v62
	v_and_b32_e32 v29, 0xffff0000, v62
	v_lshlrev_b32_e32 v30, 16, v63
	v_and_b32_e32 v31, 0xffff0000, v63
	v_pk_add_f32 v[16:17], v[16:17], v[24:25]
	v_pk_add_f32 v[18:19], v[18:19], v[26:27]
	v_pk_add_f32 v[20:21], v[20:21], v[28:29]
	v_pk_add_f32 v[22:23], v[22:23], v[30:31]
; DI unsigned pack2(float a, float b) { f2_t v = {a, b}; bf2_t r = __builtin_convertvector(v, bf2_t); return __builtin_bit_cast(unsigned, r); }
; DI float bflo(unsigned v) { return __uint_as_float(v << 16); }
; DI float bfhi(unsigned v) { return __uint_as_float(v & 0xffff0000u); }
; DI void mix_pool(WVP const u16* __restrict__ proj, u16* __restrict__ pb) {
;     ...
;     for (int i = 1; i < w; ++i) {
;       if (s0 - i >= 0) {
;         const u32x4 v = *(const u32x4*)(base - (long)i * INW);
;         a[0] += bflo(v[0]); a[1] += bfhi(v[0]); a[2] += bflo(v[1]); a[3] += bfhi(v[1]); a[4] += bflo(v[2]); a[5] += bfhi(v[2]); a[6] += bflo(v[3]); a[7] += bfhi(v[3]);
;       }
;     }
; #pragma unroll 4
;     for (int k = 0; k < 16; ++k) {
;       const int s = s0 + k;
;       const u32x4 v = *(const u32x4*)(base + (long)k * INW);
;       float u[8] = {bflo(v[0]), bfhi(v[0]), bflo(v[1]), bfhi(v[1]), bflo(v[2]), bfhi(v[2]), bflo(v[3]), bfhi(v[3])};
;       for (int q = 0; q < 8; ++q) a[q] += u[q];
;       const float ic = 1.f / (float)min(w, s + 1);
;       u32x4 o;
;       o[0] = pack2(a[0] * ic - u[0], a[1] * ic - u[1]); o[1] = pack2(a[2] * ic - u[2], a[3] * ic - u[3]);
;       o[2] = pack2(a[4] * ic - u[4], a[5] * ic - u[5]); o[3] = pack2(a[6] * ic - u[6], a[7] * ic - u[7]);
;       *(u32x4*)(pb + (long)(t0 + k) * 512 + cc * 8) = o;
;       if (s - w + 1 >= 0) {
;         const u32x4 x = *(const u32x4*)(base + (long)(k - w + 1) * INW);
;         a[0] -= bflo(x[0]); a[1] -= bfhi(x[0]); a[2] -= bflo(x[1]); a[3] -= bfhi(x[1]); a[4] -= bflo(x[2]); a[5] -= bfhi(x[2]); a[6] -= bflo(x[3]); a[7] -= bfhi(x[3]);
;       }
.Lmp_w6:
	s_mov_b64 exec, s[12:13]
	v_mov_b32_e32 v56, 0
	v_mov_b32_e32 v57, 0
	v_mov_b32_e32 v58, 0
	v_mov_b32_e32 v59, 0
	s_mov_b64 exec, -1
	v_lshlrev_b32_e32 v24, 16, v56
	v_and_b32_e32 v25, 0xffff0000, v56
	v_lshlrev_b32_e32 v26, 16, v57
	v_and_b32_e32 v27, 0xffff0000, v57
	v_lshlrev_b32_e32 v28, 16, v58
	v_and_b32_e32 v29, 0xffff0000, v58
	v_lshlrev_b32_e32 v30, 16, v59
	v_and_b32_e32 v31, 0xffff0000, v59
	v_pk_add_f32 v[16:17], v[16:17], v[24:25]
	v_pk_add_f32 v[18:19], v[18:19], v[26:27]
	v_pk_add_f32 v[20:21], v[20:21], v[28:29]
	v_pk_add_f32 v[22:23], v[22:23], v[30:31]
	s_mov_b64 exec, s[12:13]
	v_mov_b32_e32 v52, 0
	v_mov_b32_e32 v53, 0
	v_mov_b32_e32 v54, 0
	v_mov_b32_e32 v55, 0
	s_mov_b64 exec, -1
	v_lshlrev_b32_e32 v24, 16, v52
	v_and_b32_e32 v25, 0xffff0000, v52
	v_lshlrev_b32_e32 v26, 16, v53
	v_and_b32_e32 v27, 0xffff0000, v53
	v_lshlrev_b32_e32 v28, 16, v54
	v_and_b32_e32 v29, 0xffff0000, v54
	v_lshlrev_b32_e32 v30, 16, v55
	v_and_b32_e32 v31, 0xffff0000, v55
	v_pk_add_f32 v[16:17], v[16:17], v[24:25]
	v_pk_add_f32 v[18:19], v[18:19], v[26:27]
	v_pk_add_f32 v[20:21], v[20:21], v[28:29]
	v_pk_add_f32 v[22:23], v[22:23], v[30:31]
	s_mov_b64 exec, s[12:13]
	v_mov_b32_e32 v48, 0
	v_mov_b32_e32 v49, 0
	v_mov_b32_e32 v50, 0
	v_mov_b32_e32 v51, 0
	s_mov_b64 exec, -1
	v_lshlrev_b32_e32 v24, 16, v48
	v_and_b32_e32 v25, 0xffff0000, v48
	v_lshlrev_b32_e32 v26, 16, v49
	v_and_b32_e32 v27, 0xffff0000, v49
	v_lshlrev_b32_e32 v28, 16, v50
	v_and_b32_e32 v29, 0xffff0000, v50
	v_lshlrev_b32_e32 v30, 16, v51
	v_and_b32_e32 v31, 0xffff0000, v51
	v_pk_add_f32 v[16:17], v[16:17], v[24:25]
	v_pk_add_f32 v[18:19], v[18:19], v[26:27]
	v_pk_add_f32 v[20:21], v[20:21], v[28:29]
	v_pk_add_f32 v[22:23], v[22:23], v[30:31]
	s_mov_b64 exec, s[12:13]
	v_mov_b32_e32 v44, 0
	v_mov_b32_e32 v45, 0
	v_mov_b32_e32 v46, 0
	v_mov_b32_e32 v47, 0
	s_mov_b64 exec, -1
	v_lshlrev_b32_e32 v24, 16, v44
	v_and_b32_e32 v25, 0xffff0000, v44
	v_lshlrev_b32_e32 v26, 16, v45
	v_and_b32_e32 v27, 0xffff0000, v45
	v_lshlrev_b32_e32 v28, 16, v46
	v_and_b32_e32 v29, 0xffff0000, v46
	v_lshlrev_b32_e32 v30, 16, v47
	v_and_b32_e32 v31, 0xffff0000, v47
	v_pk_add_f32 v[16:17], v[16:17], v[24:25]
	v_pk_add_f32 v[18:19], v[18:19], v[26:27]
	v_pk_add_f32 v[20:21], v[20:21], v[28:29]
	v_pk_add_f32 v[22:23], v[22:23], v[30:31]
.Lmp_w2:
	s_mov_b64 exec, s[12:13]
	v_mov_b32_e32 v40, 0
	v_mov_b32_e32 v41, 0
	v_mov_b32_e32 v42, 0
	v_mov_b32_e32 v43, 0
	s_mov_b64 exec, -1
	v_lshlrev_b32_e32 v24, 16, v40
	v_and_b32_e32 v25, 0xffff0000, v40
	v_lshlrev_b32_e32 v26, 16, v41
	v_and_b32_e32 v27, 0xffff0000, v41
	v_lshlrev_b32_e32 v28, 16, v42
	v_and_b32_e32 v29, 0xffff0000, v42
	v_lshlrev_b32_e32 v30, 16, v43
	v_and_b32_e32 v31, 0xffff0000, v43
	v_pk_add_f32 v[16:17], v[16:17], v[24:25]
	v_pk_add_f32 v[18:19], v[18:19], v[26:27]
	v_pk_add_f32 v[20:21], v[20:21], v[28:29]
	v_pk_add_f32 v[22:23], v[22:23], v[30:31]
	s_mov_b64 exec, s[12:13]
	v_mov_b32_e32 v36, 0
	v_mov_b32_e32 v37, 0
	v_mov_b32_e32 v38, 0
	v_mov_b32_e32 v39, 0
	s_mov_b64 exec, -1
	v_lshlrev_b32_e32 v24, 16, v36
	v_and_b32_e32 v25, 0xffff0000, v36
	v_lshlrev_b32_e32 v26, 16, v37
	v_and_b32_e32 v27, 0xffff0000, v37
	v_lshlrev_b32_e32 v28, 16, v38
	v_and_b32_e32 v29, 0xffff0000, v38
	v_lshlrev_b32_e32 v30, 16, v39
	v_and_b32_e32 v31, 0xffff0000, v39
	v_pk_add_f32 v[16:17], v[16:17], v[24:25]
	v_pk_add_f32 v[18:19], v[18:19], v[26:27]
	v_pk_add_f32 v[20:21], v[20:21], v[28:29]
	v_pk_add_f32 v[22:23], v[22:23], v[30:31]
.Lmp_w0:
	s_mov_b64 exec, s[12:13]
	v_mov_b32_e32 v32, 0
	v_mov_b32_e32 v33, 0
	v_mov_b32_e32 v34, 0
	v_mov_b32_e32 v35, 0
	s_mov_b64 exec, -1
	v_lshlrev_b32_e32 v24, 16, v32
	v_and_b32_e32 v25, 0xffff0000, v32
	v_lshlrev_b32_e32 v26, 16, v33
	v_and_b32_e32 v27, 0xffff0000, v33
	v_lshlrev_b32_e32 v28, 16, v34
	v_and_b32_e32 v29, 0xffff0000, v34
	v_lshlrev_b32_e32 v30, 16, v35
	v_and_b32_e32 v31, 0xffff0000, v35
	v_pk_add_f32 v[16:17], v[16:17], v[24:25]
	v_pk_add_f32 v[18:19], v[18:19], v[26:27]
	v_pk_add_f32 v[20:21], v[20:21], v[28:29]
	v_pk_add_f32 v[22:23], v[22:23], v[30:31]
	s_waitcnt vmcnt(15)
	v_lshlrev_b32_e32 v24, 16, v92
	v_and_b32_e32 v25, 0xffff0000, v92
	v_lshlrev_b32_e32 v26, 16, v93
	v_and_b32_e32 v27, 0xffff0000, v93
	v_lshlrev_b32_e32 v28, 16, v94
	v_and_b32_e32 v29, 0xffff0000, v94
	v_lshlrev_b32_e32 v30, 16, v95
	v_and_b32_e32 v31, 0xffff0000, v95
	v_pk_add_f32 v[16:17], v[16:17], v[24:25]
	v_pk_add_f32 v[18:19], v[18:19], v[26:27]
	v_pk_add_f32 v[20:21], v[20:21], v[28:29]
	v_pk_add_f32 v[22:23], v[22:23], v[30:31]
	s_cmp_lt_u32 1, s4
	s_cselect_b32 s11, 0x3f800000, s10
	v_mov_b32_e32 v5, s11
	v_cndmask_b32_e64 v2, v4, v5, s[12:13]
	v_pk_fma_f32 v[8:9], v[2:3], v[16:17], v[24:25] op_sel_hi:[0,1,1] neg_lo:[0,0,1] neg_hi:[0,0,1]
	v_pk_fma_f32 v[10:11], v[2:3], v[18:19], v[26:27] op_sel_hi:[0,1,1] neg_lo:[0,0,1] neg_hi:[0,0,1]
	v_pk_fma_f32 v[12:13], v[2:3], v[20:21], v[28:29] op_sel_hi:[0,1,1] neg_lo:[0,0,1] neg_hi:[0,0,1]
	v_pk_fma_f32 v[14:15], v[2:3], v[22:23], v[30:31] op_sel_hi:[0,1,1] neg_lo:[0,0,1] neg_hi:[0,0,1]
	v_cvt_pk_bf16_f32 v8, v8, v9
	v_cvt_pk_bf16_f32 v9, v10, v11
	v_cvt_pk_bf16_f32 v10, v12, v13
	v_cvt_pk_bf16_f32 v11, v14, v15
	global_store_dwordx4 v7, v[8:11], s[18:19]
	s_add_u32 s18, s18, 0x400
	s_addc_u32 s19, s19, 0
	v_lshlrev_b32_e32 v24, 16, v32
	v_and_b32_e32 v25, 0xffff0000, v32
	v_lshlrev_b32_e32 v26, 16, v33
	v_and_b32_e32 v27, 0xffff0000, v33
	v_lshlrev_b32_e32 v28, 16, v34
	v_and_b32_e32 v29, 0xffff0000, v34
	v_lshlrev_b32_e32 v30, 16, v35
	v_and_b32_e32 v31, 0xffff0000, v35
	v_pk_add_f32 v[16:17], v[16:17], v[24:25] neg_lo:[0,1] neg_hi:[0,1]
	v_pk_add_f32 v[18:19], v[18:19], v[26:27] neg_lo:[0,1] neg_hi:[0,1]
	v_pk_add_f32 v[20:21], v[20:21], v[28:29] neg_lo:[0,1] neg_hi:[0,1]
	v_pk_add_f32 v[22:23], v[22:23], v[30:31] neg_lo:[0,1] neg_hi:[0,1]
	s_waitcnt vmcnt(15)
; DI unsigned pack2(float a, float b) { f2_t v = {a, b}; bf2_t r = __builtin_convertvector(v, bf2_t); return __builtin_bit_cast(unsigned, r); }
; DI float bflo(unsigned v) { return __uint_as_float(v << 16); }
; DI float bfhi(unsigned v) { return __uint_as_float(v & 0xffff0000u); }
; DI void mix_pool(WVP const u16* __restrict__ proj, u16* __restrict__ pb) {
;     ...
;     for (int k = 0; k < 16; ++k) {
;       const int s = s0 + k;
;       const u32x4 v = *(const u32x4*)(base + (long)k * INW);
;       float u[8] = {bflo(v[0]), bfhi(v[0]), bflo(v[1]), bfhi(v[1]), bflo(v[2]), bfhi(v[2]), bflo(v[3]), bfhi(v[3])};
;       for (int q = 0; q < 8; ++q) a[q] += u[q];
;       const float ic = 1.f / (float)min(w, s + 1);
;       u32x4 o;
;       o[0] = pack2(a[0] * ic - u[0], a[1] * ic - u[1]); o[1] = pack2(a[2] * ic - u[2], a[3] * ic - u[3]);
;       o[2] = pack2(a[4] * ic - u[4], a[5] * ic - u[5]); o[3] = pack2(a[6] * ic - u[6], a[7] * ic - u[7]);
;       *(u32x4*)(pb + (long)(t0 + k) * 512 + cc * 8) = o;
;       if (s - w + 1 >= 0) {
;         const u32x4 x = *(const u32x4*)(base + (long)(k - w + 1) * INW);
;         a[0] -= bflo(x[0]); a[1] -= bfhi(x[0]); a[2] -= bflo(x[1]); a[3] -= bfhi(x[1]); a[4] -= bflo(x[2]); a[5] -= bfhi(x[2]); a[6] -= bflo(x[3]); a[7] -= bfhi(x[3]);
;       }
	v_lshlrev_b32_e32 v24, 16, v96
	v_and_b32_e32 v25, 0xffff0000, v96
	v_lshlrev_b32_e32 v26, 16, v97
	v_and_b32_e32 v27, 0xffff0000, v97
	v_lshlrev_b32_e32 v28, 16, v98
	v_and_b32_e32 v29, 0xffff0000, v98
	v_lshlrev_b32_e32 v30, 16, v99
	v_and_b32_e32 v31, 0xffff0000, v99
	v_pk_add_f32 v[16:17], v[16:17], v[24:25]
	v_pk_add_f32 v[18:19], v[18:19], v[26:27]
	v_pk_add_f32 v[20:21], v[20:21], v[28:29]
	v_pk_add_f32 v[22:23], v[22:23], v[30:31]
	s_cmp_lt_u32 2, s4
	s_cselect_b32 s11, 0x3f000000, s10
	v_mov_b32_e32 v5, s11
	v_cndmask_b32_e64 v2, v4, v5, s[12:13]
	v_pk_fma_f32 v[8:9], v[2:3], v[16:17], v[24:25] op_sel_hi:[0,1,1] neg_lo:[0,0,1] neg_hi:[0,0,1]
	v_pk_fma_f32 v[10:11], v[2:3], v[18:19], v[26:27] op_sel_hi:[0,1,1] neg_lo:[0,0,1] neg_hi:[0,0,1]
	v_pk_fma_f32 v[12:13], v[2:3], v[20:21], v[28:29] op_sel_hi:[0,1,1] neg_lo:[0,0,1] neg_hi:[0,0,1]
	v_pk_fma_f32 v[14:15], v[2:3], v[22:23], v[30:31] op_sel_hi:[0,1,1] neg_lo:[0,0,1] neg_hi:[0,0,1]
	v_cvt_pk_bf16_f32 v8, v8, v9
	v_cvt_pk_bf16_f32 v9, v10, v11
	v_cvt_pk_bf16_f32 v10, v12, v13
	v_cvt_pk_bf16_f32 v11, v14, v15
	global_store_dwordx4 v7, v[8:11], s[18:19]
	s_add_u32 s18, s18, 0x400
	s_addc_u32 s19, s19, 0
	v_lshlrev_b32_e32 v24, 16, v36
	v_and_b32_e32 v25, 0xffff0000, v36
	v_lshlrev_b32_e32 v26, 16, v37
	v_and_b32_e32 v27, 0xffff0000, v37
	v_lshlrev_b32_e32 v28, 16, v38
	v_and_b32_e32 v29, 0xffff0000, v38
	v_lshlrev_b32_e32 v30, 16, v39
	v_and_b32_e32 v31, 0xffff0000, v39
	v_pk_add_f32 v[16:17], v[16:17], v[24:25] neg_lo:[0,1] neg_hi:[0,1]
	v_pk_add_f32 v[18:19], v[18:19], v[26:27] neg_lo:[0,1] neg_hi:[0,1]
	v_pk_add_f32 v[20:21], v[20:21], v[28:29] neg_lo:[0,1] neg_hi:[0,1]
	v_pk_add_f32 v[22:23], v[22:23], v[30:31] neg_lo:[0,1] neg_hi:[0,1]
	s_waitcnt vmcnt(15)
	v_lshlrev_b32_e32 v24, 16, v100
	v_and_b32_e32 v25, 0xffff0000, v100
	v_lshlrev_b32_e32 v26, 16, v101
	v_and_b32_e32 v27, 0xffff0000, v101
	v_lshlrev_b32_e32 v28, 16, v102
	v_and_b32_e32 v29, 0xffff0000, v102
	v_lshlrev_b32_e32 v30, 16, v103
	v_and_b32_e32 v31, 0xffff0000, v103
	v_pk_add_f32 v[16:17], v[16:17], v[24:25]
	v_pk_add_f32 v[18:19], v[18:19], v[26:27]
	v_pk_add_f32 v[20:21], v[20:21], v[28:29]
	v_pk_add_f32 v[22:23], v[22:23], v[30:31]
	s_cmp_lt_u32 3, s4
	s_cselect_b32 s11, 0x3eaaaaab, s10
	v_mov_b32_e32 v5, s11
	v_cndmask_b32_e64 v2, v4, v5, s[12:13]
	v_pk_fma_f32 v[8:9], v[2:3], v[16:17], v[24:25] op_sel_hi:[0,1,1] neg_lo:[0,0,1] neg_hi:[0,0,1]
	v_pk_fma_f32 v[10:11], v[2:3], v[18:19], v[26:27] op_sel_hi:[0,1,1] neg_lo:[0,0,1] neg_hi:[0,0,1]
	v_pk_fma_f32 v[12:13], v[2:3], v[20:21], v[28:29] op_sel_hi:[0,1,1] neg_lo:[0,0,1] neg_hi:[0,0,1]
	v_pk_fma_f32 v[14:15], v[2:3], v[22:23], v[30:31] op_sel_hi:[0,1,1] neg_lo:[0,0,1] neg_hi:[0,0,1]
	v_cvt_pk_bf16_f32 v8, v8, v9
	v_cvt_pk_bf16_f32 v9, v10, v11
	v_cvt_pk_bf16_f32 v10, v12, v13
	v_cvt_pk_bf16_f32 v11, v14, v15
	global_store_dwordx4 v7, v[8:11], s[18:19]
	s_add_u32 s18, s18, 0x400
	s_addc_u32 s19, s19, 0
	v_lshlrev_b32_e32 v24, 16, v40
	v_and_b32_e32 v25, 0xffff0000, v40
	v_lshlrev_b32_e32 v26, 16, v41
	v_and_b32_e32 v27, 0xffff0000, v41
	v_lshlrev_b32_e32 v28, 16, v42
	v_and_b32_e32 v29, 0xffff0000, v42
	v_lshlrev_b32_e32 v30, 16, v43
	v_and_b32_e32 v31, 0xffff0000, v43
	v_pk_add_f32 v[16:17], v[16:17], v[24:25] neg_lo:[0,1] neg_hi:[0,1]
	v_pk_add_f32 v[18:19], v[18:19], v[26:27] neg_lo:[0,1] neg_hi:[0,1]
	v_pk_add_f32 v[20:21], v[20:21], v[28:29] neg_lo:[0,1] neg_hi:[0,1]
	v_pk_add_f32 v[22:23], v[22:23], v[30:31] neg_lo:[0,1] neg_hi:[0,1]
	s_waitcnt vmcnt(15)
	v_lshlrev_b32_e32 v24, 16, v104
	v_and_b32_e32 v25, 0xffff0000, v104
	v_lshlrev_b32_e32 v26, 16, v105
	v_and_b32_e32 v27, 0xffff0000, v105
	v_lshlrev_b32_e32 v28, 16, v106
	v_and_b32_e32 v29, 0xffff0000, v106
	v_lshlrev_b32_e32 v30, 16, v107
	v_and_b32_e32 v31, 0xffff0000, v107
	v_pk_add_f32 v[16:17], v[16:17], v[24:25]
	v_pk_add_f32 v[18:19], v[18:19], v[26:27]
	v_pk_add_f32 v[20:21], v[20:21], v[28:29]
	v_pk_add_f32 v[22:23], v[22:23], v[30:31]
	s_cmp_lt_u32 4, s4
	s_cselect_b32 s11, 0x3e800000, s10
	v_mov_b32_e32 v5, s11
	v_cndmask_b32_e64 v2, v4, v5, s[12:13]
	v_pk_fma_f32 v[8:9], v[2:3], v[16:17], v[24:25] op_sel_hi:[0,1,1] neg_lo:[0,0,1] neg_hi:[0,0,1]
	v_pk_fma_f32 v[10:11], v[2:3], v[18:19], v[26:27] op_sel_hi:[0,1,1] neg_lo:[0,0,1] neg_hi:[0,0,1]
	v_pk_fma_f32 v[12:13], v[2:3], v[20:21], v[28:29] op_sel_hi:[0,1,1] neg_lo:[0,0,1] neg_hi:[0,0,1]
	v_pk_fma_f32 v[14:15], v[2:3], v[22:23], v[30:31] op_sel_hi:[0,1,1] neg_lo:[0,0,1] neg_hi:[0,0,1]
	v_cvt_pk_bf16_f32 v8, v8, v9
	v_cvt_pk_bf16_f32 v9, v10, v11
	v_cvt_pk_bf16_f32 v10, v12, v13
	v_cvt_pk_bf16_f32 v11, v14, v15
	global_store_dwordx4 v7, v[8:11], s[18:19]
	s_add_u32 s18, s18, 0x400
	s_addc_u32 s19, s19, 0
	v_lshlrev_b32_e32 v24, 16, v44
	v_and_b32_e32 v25, 0xffff0000, v44
	v_lshlrev_b32_e32 v26, 16, v45
	v_and_b32_e32 v27, 0xffff0000, v45
	v_lshlrev_b32_e32 v28, 16, v46
	v_and_b32_e32 v29, 0xffff0000, v46
	v_lshlrev_b32_e32 v30, 16, v47
	v_and_b32_e32 v31, 0xffff0000, v47
	v_pk_add_f32 v[16:17], v[16:17], v[24:25] neg_lo:[0,1] neg_hi:[0,1]
	v_pk_add_f32 v[18:19], v[18:19], v[26:27] neg_lo:[0,1] neg_hi:[0,1]
	v_pk_add_f32 v[20:21], v[20:21], v[28:29] neg_lo:[0,1] neg_hi:[0,1]
	v_pk_add_f32 v[22:23], v[22:23], v[30:31] neg_lo:[0,1] neg_hi:[0,1]
	s_waitcnt vmcnt(15)
; DI unsigned pack2(float a, float b) { f2_t v = {a, b}; bf2_t r = __builtin_convertvector(v, bf2_t); return __builtin_bit_cast(unsigned, r); }
; DI float bflo(unsigned v) { return __uint_as_float(v << 16); }
; DI float bfhi(unsigned v) { return __uint_as_float(v & 0xffff0000u); }
; DI void mix_pool(WVP const u16* __restrict__ proj, u16* __restrict__ pb) {
;     ...
;     for (int k = 0; k < 16; ++k) {
;       const int s = s0 + k;
;       const u32x4 v = *(const u32x4*)(base + (long)k * INW);
;       float u[8] = {bflo(v[0]), bfhi(v[0]), bflo(v[1]), bfhi(v[1]), bflo(v[2]), bfhi(v[2]), bflo(v[3]), bfhi(v[3])};
;       for (int q = 0; q < 8; ++q) a[q] += u[q];
;       const float ic = 1.f / (float)min(w, s + 1);
;       u32x4 o;
;       o[0] = pack2(a[0] * ic - u[0], a[1] * ic - u[1]); o[1] = pack2(a[2] * ic - u[2], a[3] * ic - u[3]);
;       o[2] = pack2(a[4] * ic - u[4], a[5] * ic - u[5]); o[3] = pack2(a[6] * ic - u[6], a[7] * ic - u[7]);
;       *(u32x4*)(pb + (long)(t0 + k) * 512 + cc * 8) = o;
;       if (s - w + 1 >= 0) {
;         const u32x4 x = *(const u32x4*)(base + (long)(k - w + 1) * INW);
;         a[0] -= bflo(x[0]); a[1] -= bfhi(x[0]); a[2] -= bflo(x[1]); a[3] -= bfhi(x[1]); a[4] -= bflo(x[2]); a[5] -= bfhi(x[2]); a[6] -= bflo(x[3]); a[7] -= bfhi(x[3]);
;       }
	v_lshlrev_b32_e32 v24, 16, v108
	v_and_b32_e32 v25, 0xffff0000, v108
	v_lshlrev_b32_e32 v26, 16, v109
	v_and_b32_e32 v27, 0xffff0000, v109
	v_lshlrev_b32_e32 v28, 16, v110
	v_and_b32_e32 v29, 0xffff0000, v110
	v_lshlrev_b32_e32 v30, 16, v111
	v_and_b32_e32 v31, 0xffff0000, v111
	v_pk_add_f32 v[16:17], v[16:17], v[24:25]
	v_pk_add_f32 v[18:19], v[18:19], v[26:27]
	v_pk_add_f32 v[20:21], v[20:21], v[28:29]
	v_pk_add_f32 v[22:23], v[22:23], v[30:31]
	s_cmp_lt_u32 5, s4
	s_cselect_b32 s11, 0x3e4ccccd, s10
	v_mov_b32_e32 v5, s11
	v_cndmask_b32_e64 v2, v4, v5, s[12:13]
	v_pk_fma_f32 v[8:9], v[2:3], v[16:17], v[24:25] op_sel_hi:[0,1,1] neg_lo:[0,0,1] neg_hi:[0,0,1]
	v_pk_fma_f32 v[10:11], v[2:3], v[18:19], v[26:27] op_sel_hi:[0,1,1] neg_lo:[0,0,1] neg_hi:[0,0,1]
	v_pk_fma_f32 v[12:13], v[2:3], v[20:21], v[28:29] op_sel_hi:[0,1,1] neg_lo:[0,0,1] neg_hi:[0,0,1]
	v_pk_fma_f32 v[14:15], v[2:3], v[22:23], v[30:31] op_sel_hi:[0,1,1] neg_lo:[0,0,1] neg_hi:[0,0,1]
	v_cvt_pk_bf16_f32 v8, v8, v9
	v_cvt_pk_bf16_f32 v9, v10, v11
	v_cvt_pk_bf16_f32 v10, v12, v13
	v_cvt_pk_bf16_f32 v11, v14, v15
	global_store_dwordx4 v7, v[8:11], s[18:19]
	s_add_u32 s18, s18, 0x400
	s_addc_u32 s19, s19, 0
	v_lshlrev_b32_e32 v24, 16, v48
	v_and_b32_e32 v25, 0xffff0000, v48
	v_lshlrev_b32_e32 v26, 16, v49
	v_and_b32_e32 v27, 0xffff0000, v49
	v_lshlrev_b32_e32 v28, 16, v50
	v_and_b32_e32 v29, 0xffff0000, v50
	v_lshlrev_b32_e32 v30, 16, v51
	v_and_b32_e32 v31, 0xffff0000, v51
	v_pk_add_f32 v[16:17], v[16:17], v[24:25] neg_lo:[0,1] neg_hi:[0,1]
	v_pk_add_f32 v[18:19], v[18:19], v[26:27] neg_lo:[0,1] neg_hi:[0,1]
	v_pk_add_f32 v[20:21], v[20:21], v[28:29] neg_lo:[0,1] neg_hi:[0,1]
	v_pk_add_f32 v[22:23], v[22:23], v[30:31] neg_lo:[0,1] neg_hi:[0,1]
	s_waitcnt vmcnt(15)
	v_lshlrev_b32_e32 v24, 16, v112
	v_and_b32_e32 v25, 0xffff0000, v112
	v_lshlrev_b32_e32 v26, 16, v113
	v_and_b32_e32 v27, 0xffff0000, v113
	v_lshlrev_b32_e32 v28, 16, v114
	v_and_b32_e32 v29, 0xffff0000, v114
	v_lshlrev_b32_e32 v30, 16, v115
	v_and_b32_e32 v31, 0xffff0000, v115
	v_pk_add_f32 v[16:17], v[16:17], v[24:25]
	v_pk_add_f32 v[18:19], v[18:19], v[26:27]
	v_pk_add_f32 v[20:21], v[20:21], v[28:29]
	v_pk_add_f32 v[22:23], v[22:23], v[30:31]
	s_cmp_lt_u32 6, s4
	s_cselect_b32 s11, 0x3e2aaaab, s10
	v_mov_b32_e32 v5, s11
	v_cndmask_b32_e64 v2, v4, v5, s[12:13]
	v_pk_fma_f32 v[8:9], v[2:3], v[16:17], v[24:25] op_sel_hi:[0,1,1] neg_lo:[0,0,1] neg_hi:[0,0,1]
	v_pk_fma_f32 v[10:11], v[2:3], v[18:19], v[26:27] op_sel_hi:[0,1,1] neg_lo:[0,0,1] neg_hi:[0,0,1]
	v_pk_fma_f32 v[12:13], v[2:3], v[20:21], v[28:29] op_sel_hi:[0,1,1] neg_lo:[0,0,1] neg_hi:[0,0,1]
	v_pk_fma_f32 v[14:15], v[2:3], v[22:23], v[30:31] op_sel_hi:[0,1,1] neg_lo:[0,0,1] neg_hi:[0,0,1]
	v_cvt_pk_bf16_f32 v8, v8, v9
	v_cvt_pk_bf16_f32 v9, v10, v11
	v_cvt_pk_bf16_f32 v10, v12, v13
	v_cvt_pk_bf16_f32 v11, v14, v15
	global_store_dwordx4 v7, v[8:11], s[18:19]
	s_add_u32 s18, s18, 0x400
	s_addc_u32 s19, s19, 0
	v_lshlrev_b32_e32 v24, 16, v52
	v_and_b32_e32 v25, 0xffff0000, v52
	v_lshlrev_b32_e32 v26, 16, v53
	v_and_b32_e32 v27, 0xffff0000, v53
	v_lshlrev_b32_e32 v28, 16, v54
	v_and_b32_e32 v29, 0xffff0000, v54
	v_lshlrev_b32_e32 v30, 16, v55
	v_and_b32_e32 v31, 0xffff0000, v55
	v_pk_add_f32 v[16:17], v[16:17], v[24:25] neg_lo:[0,1] neg_hi:[0,1]
	v_pk_add_f32 v[18:19], v[18:19], v[26:27] neg_lo:[0,1] neg_hi:[0,1]
	v_pk_add_f32 v[20:21], v[20:21], v[28:29] neg_lo:[0,1] neg_hi:[0,1]
	v_pk_add_f32 v[22:23], v[22:23], v[30:31] neg_lo:[0,1] neg_hi:[0,1]
	s_waitcnt vmcnt(15)
	v_lshlrev_b32_e32 v24, 16, v116
	v_and_b32_e32 v25, 0xffff0000, v116
	v_lshlrev_b32_e32 v26, 16, v117
	v_and_b32_e32 v27, 0xffff0000, v117
	v_lshlrev_b32_e32 v28, 16, v118
	v_and_b32_e32 v29, 0xffff0000, v118
	v_lshlrev_b32_e32 v30, 16, v119
	v_and_b32_e32 v31, 0xffff0000, v119
	v_pk_add_f32 v[16:17], v[16:17], v[24:25]
	v_pk_add_f32 v[18:19], v[18:19], v[26:27]
	v_pk_add_f32 v[20:21], v[20:21], v[28:29]
	v_pk_add_f32 v[22:23], v[22:23], v[30:31]
	s_cmp_lt_u32 7, s4
	s_cselect_b32 s11, 0x3e124925, s10
	v_mov_b32_e32 v5, s11
	v_cndmask_b32_e64 v2, v4, v5, s[12:13]
	v_pk_fma_f32 v[8:9], v[2:3], v[16:17], v[24:25] op_sel_hi:[0,1,1] neg_lo:[0,0,1] neg_hi:[0,0,1]
	v_pk_fma_f32 v[10:11], v[2:3], v[18:19], v[26:27] op_sel_hi:[0,1,1] neg_lo:[0,0,1] neg_hi:[0,0,1]
	v_pk_fma_f32 v[12:13], v[2:3], v[20:21], v[28:29] op_sel_hi:[0,1,1] neg_lo:[0,0,1] neg_hi:[0,0,1]
	v_pk_fma_f32 v[14:15], v[2:3], v[22:23], v[30:31] op_sel_hi:[0,1,1] neg_lo:[0,0,1] neg_hi:[0,0,1]
	v_cvt_pk_bf16_f32 v8, v8, v9
	v_cvt_pk_bf16_f32 v9, v10, v11
	v_cvt_pk_bf16_f32 v10, v12, v13
	v_cvt_pk_bf16_f32 v11, v14, v15
	global_store_dwordx4 v7, v[8:11], s[18:19]
	s_add_u32 s18, s18, 0x400
	s_addc_u32 s19, s19, 0
	v_lshlrev_b32_e32 v24, 16, v56
	v_and_b32_e32 v25, 0xffff0000, v56
	v_lshlrev_b32_e32 v26, 16, v57
	v_and_b32_e32 v27, 0xffff0000, v57
	v_lshlrev_b32_e32 v28, 16, v58
	v_and_b32_e32 v29, 0xffff0000, v58
	v_lshlrev_b32_e32 v30, 16, v59
	v_and_b32_e32 v31, 0xffff0000, v59
	v_pk_add_f32 v[16:17], v[16:17], v[24:25] neg_lo:[0,1] neg_hi:[0,1]
	v_pk_add_f32 v[18:19], v[18:19], v[26:27] neg_lo:[0,1] neg_hi:[0,1]
	v_pk_add_f32 v[20:21], v[20:21], v[28:29] neg_lo:[0,1] neg_hi:[0,1]
	v_pk_add_f32 v[22:23], v[22:23], v[30:31] neg_lo:[0,1] neg_hi:[0,1]
	s_waitcnt vmcnt(15)
; DI unsigned pack2(float a, float b) { f2_t v = {a, b}; bf2_t r = __builtin_convertvector(v, bf2_t); return __builtin_bit_cast(unsigned, r); }
; DI float bflo(unsigned v) { return __uint_as_float(v << 16); }
; DI float bfhi(unsigned v) { return __uint_as_float(v & 0xffff0000u); }
; DI void mix_pool(WVP const u16* __restrict__ proj, u16* __restrict__ pb) {
;     ...
;     for (int k = 0; k < 16; ++k) {
;       const int s = s0 + k;
;       const u32x4 v = *(const u32x4*)(base + (long)k * INW);
;       float u[8] = {bflo(v[0]), bfhi(v[0]), bflo(v[1]), bfhi(v[1]), bflo(v[2]), bfhi(v[2]), bflo(v[3]), bfhi(v[3])};
;       for (int q = 0; q < 8; ++q) a[q] += u[q];
;       const float ic = 1.f / (float)min(w, s + 1);
;       u32x4 o;
;       o[0] = pack2(a[0] * ic - u[0], a[1] * ic - u[1]); o[1] = pack2(a[2] * ic - u[2], a[3] * ic - u[3]);
;       o[2] = pack2(a[4] * ic - u[4], a[5] * ic - u[5]); o[3] = pack2(a[6] * ic - u[6], a[7] * ic - u[7]);
;       *(u32x4*)(pb + (long)(t0 + k) * 512 + cc * 8) = o;
;       if (s - w + 1 >= 0) {
;         const u32x4 x = *(const u32x4*)(base + (long)(k - w + 1) * INW);
;         a[0] -= bflo(x[0]); a[1] -= bfhi(x[0]); a[2] -= bflo(x[1]); a[3] -= bfhi(x[1]); a[4] -= bflo(x[2]); a[5] -= bfhi(x[2]); a[6] -= bflo(x[3]); a[7] -= bfhi(x[3]);
;       }
	v_lshlrev_b32_e32 v24, 16, v120
	v_and_b32_e32 v25, 0xffff0000, v120
	v_lshlrev_b32_e32 v26, 16, v121
	v_and_b32_e32 v27, 0xffff0000, v121
	v_lshlrev_b32_e32 v28, 16, v122
	v_and_b32_e32 v29, 0xffff0000, v122
	v_lshlrev_b32_e32 v30, 16, v123
	v_and_b32_e32 v31, 0xffff0000, v123
	v_pk_add_f32 v[16:17], v[16:17], v[24:25]
	v_pk_add_f32 v[18:19], v[18:19], v[26:27]
	v_pk_add_f32 v[20:21], v[20:21], v[28:29]
	v_pk_add_f32 v[22:23], v[22:23], v[30:31]
	s_cmp_lt_u32 8, s4
	s_cselect_b32 s11, 0x3e000000, s10
	v_mov_b32_e32 v5, s11
	v_cndmask_b32_e64 v2, v4, v5, s[12:13]
	v_pk_fma_f32 v[8:9], v[2:3], v[16:17], v[24:25] op_sel_hi:[0,1,1] neg_lo:[0,0,1] neg_hi:[0,0,1]
	v_pk_fma_f32 v[10:11], v[2:3], v[18:19], v[26:27] op_sel_hi:[0,1,1] neg_lo:[0,0,1] neg_hi:[0,0,1]
	v_pk_fma_f32 v[12:13], v[2:3], v[20:21], v[28:29] op_sel_hi:[0,1,1] neg_lo:[0,0,1] neg_hi:[0,0,1]
	v_pk_fma_f32 v[14:15], v[2:3], v[22:23], v[30:31] op_sel_hi:[0,1,1] neg_lo:[0,0,1] neg_hi:[0,0,1]
	v_cvt_pk_bf16_f32 v8, v8, v9
	v_cvt_pk_bf16_f32 v9, v10, v11
	v_cvt_pk_bf16_f32 v10, v12, v13
	v_cvt_pk_bf16_f32 v11, v14, v15
	global_store_dwordx4 v7, v[8:11], s[18:19]
	s_add_u32 s18, s18, 0x400
	s_addc_u32 s19, s19, 0
	v_lshlrev_b32_e32 v24, 16, v60
	v_and_b32_e32 v25, 0xffff0000, v60
	v_lshlrev_b32_e32 v26, 16, v61
	v_and_b32_e32 v27, 0xffff0000, v61
	v_lshlrev_b32_e32 v28, 16, v62
	v_and_b32_e32 v29, 0xffff0000, v62
	v_lshlrev_b32_e32 v30, 16, v63
	v_and_b32_e32 v31, 0xffff0000, v63
	v_pk_add_f32 v[16:17], v[16:17], v[24:25] neg_lo:[0,1] neg_hi:[0,1]
	v_pk_add_f32 v[18:19], v[18:19], v[26:27] neg_lo:[0,1] neg_hi:[0,1]
	v_pk_add_f32 v[20:21], v[20:21], v[28:29] neg_lo:[0,1] neg_hi:[0,1]
	v_pk_add_f32 v[22:23], v[22:23], v[30:31] neg_lo:[0,1] neg_hi:[0,1]
	s_waitcnt vmcnt(15)
	v_lshlrev_b32_e32 v24, 16, v124
	v_and_b32_e32 v25, 0xffff0000, v124
	v_lshlrev_b32_e32 v26, 16, v125
	v_and_b32_e32 v27, 0xffff0000, v125
	v_lshlrev_b32_e32 v28, 16, v126
	v_and_b32_e32 v29, 0xffff0000, v126
	v_lshlrev_b32_e32 v30, 16, v127
	v_and_b32_e32 v31, 0xffff0000, v127
	v_pk_add_f32 v[16:17], v[16:17], v[24:25]
	v_pk_add_f32 v[18:19], v[18:19], v[26:27]
	v_pk_add_f32 v[20:21], v[20:21], v[28:29]
	v_pk_add_f32 v[22:23], v[22:23], v[30:31]
	s_cmp_lt_u32 9, s4
	s_cselect_b32 s11, 0x3de38e39, s10
	v_mov_b32_e32 v5, s11
	v_cndmask_b32_e64 v2, v4, v5, s[12:13]
	v_pk_fma_f32 v[8:9], v[2:3], v[16:17], v[24:25] op_sel_hi:[0,1,1] neg_lo:[0,0,1] neg_hi:[0,0,1]
	v_pk_fma_f32 v[10:11], v[2:3], v[18:19], v[26:27] op_sel_hi:[0,1,1] neg_lo:[0,0,1] neg_hi:[0,0,1]
	v_pk_fma_f32 v[12:13], v[2:3], v[20:21], v[28:29] op_sel_hi:[0,1,1] neg_lo:[0,0,1] neg_hi:[0,0,1]
	v_pk_fma_f32 v[14:15], v[2:3], v[22:23], v[30:31] op_sel_hi:[0,1,1] neg_lo:[0,0,1] neg_hi:[0,0,1]
	v_cvt_pk_bf16_f32 v8, v8, v9
	v_cvt_pk_bf16_f32 v9, v10, v11
	v_cvt_pk_bf16_f32 v10, v12, v13
	v_cvt_pk_bf16_f32 v11, v14, v15
	global_store_dwordx4 v7, v[8:11], s[18:19]
	s_add_u32 s18, s18, 0x400
	s_addc_u32 s19, s19, 0
	v_lshlrev_b32_e32 v24, 16, v64
	v_and_b32_e32 v25, 0xffff0000, v64
	v_lshlrev_b32_e32 v26, 16, v65
	v_and_b32_e32 v27, 0xffff0000, v65
	v_lshlrev_b32_e32 v28, 16, v66
	v_and_b32_e32 v29, 0xffff0000, v66
	v_lshlrev_b32_e32 v30, 16, v67
	v_and_b32_e32 v31, 0xffff0000, v67
	v_pk_add_f32 v[16:17], v[16:17], v[24:25] neg_lo:[0,1] neg_hi:[0,1]
	v_pk_add_f32 v[18:19], v[18:19], v[26:27] neg_lo:[0,1] neg_hi:[0,1]
	v_pk_add_f32 v[20:21], v[20:21], v[28:29] neg_lo:[0,1] neg_hi:[0,1]
	v_pk_add_f32 v[22:23], v[22:23], v[30:31] neg_lo:[0,1] neg_hi:[0,1]
	s_waitcnt vmcnt(15)
	v_lshlrev_b32_e32 v24, 16, v128
	v_and_b32_e32 v25, 0xffff0000, v128
	v_lshlrev_b32_e32 v26, 16, v129
	v_and_b32_e32 v27, 0xffff0000, v129
	v_lshlrev_b32_e32 v28, 16, v130
	v_and_b32_e32 v29, 0xffff0000, v130
	v_lshlrev_b32_e32 v30, 16, v131
	v_and_b32_e32 v31, 0xffff0000, v131
	v_pk_add_f32 v[16:17], v[16:17], v[24:25]
	v_pk_add_f32 v[18:19], v[18:19], v[26:27]
	v_pk_add_f32 v[20:21], v[20:21], v[28:29]
	v_pk_add_f32 v[22:23], v[22:23], v[30:31]
	s_cmp_lt_u32 10, s4
	s_cselect_b32 s11, 0x3dcccccd, s10
	v_mov_b32_e32 v5, s11
	v_cndmask_b32_e64 v2, v4, v5, s[12:13]
	v_pk_fma_f32 v[8:9], v[2:3], v[16:17], v[24:25] op_sel_hi:[0,1,1] neg_lo:[0,0,1] neg_hi:[0,0,1]
	v_pk_fma_f32 v[10:11], v[2:3], v[18:19], v[26:27] op_sel_hi:[0,1,1] neg_lo:[0,0,1] neg_hi:[0,0,1]
	v_pk_fma_f32 v[12:13], v[2:3], v[20:21], v[28:29] op_sel_hi:[0,1,1] neg_lo:[0,0,1] neg_hi:[0,0,1]
	v_pk_fma_f32 v[14:15], v[2:3], v[22:23], v[30:31] op_sel_hi:[0,1,1] neg_lo:[0,0,1] neg_hi:[0,0,1]
	v_cvt_pk_bf16_f32 v8, v8, v9
	v_cvt_pk_bf16_f32 v9, v10, v11
	v_cvt_pk_bf16_f32 v10, v12, v13
	v_cvt_pk_bf16_f32 v11, v14, v15
	global_store_dwordx4 v7, v[8:11], s[18:19]
	s_add_u32 s18, s18, 0x400
	s_addc_u32 s19, s19, 0
	v_lshlrev_b32_e32 v24, 16, v68
	v_and_b32_e32 v25, 0xffff0000, v68
	v_lshlrev_b32_e32 v26, 16, v69
	v_and_b32_e32 v27, 0xffff0000, v69
	v_lshlrev_b32_e32 v28, 16, v70
	v_and_b32_e32 v29, 0xffff0000, v70
	v_lshlrev_b32_e32 v30, 16, v71
	v_and_b32_e32 v31, 0xffff0000, v71
	v_pk_add_f32 v[16:17], v[16:17], v[24:25] neg_lo:[0,1] neg_hi:[0,1]
	v_pk_add_f32 v[18:19], v[18:19], v[26:27] neg_lo:[0,1] neg_hi:[0,1]
	v_pk_add_f32 v[20:21], v[20:21], v[28:29] neg_lo:[0,1] neg_hi:[0,1]
	v_pk_add_f32 v[22:23], v[22:23], v[30:31] neg_lo:[0,1] neg_hi:[0,1]
	s_waitcnt vmcnt(15)
; DI unsigned pack2(float a, float b) { f2_t v = {a, b}; bf2_t r = __builtin_convertvector(v, bf2_t); return __builtin_bit_cast(unsigned, r); }
; DI float bflo(unsigned v) { return __uint_as_float(v << 16); }
; DI float bfhi(unsigned v) { return __uint_as_float(v & 0xffff0000u); }
; DI void mix_pool(WVP const u16* __restrict__ proj, u16* __restrict__ pb) {
;     ...
;     for (int k = 0; k < 16; ++k) {
;       const int s = s0 + k;
;       const u32x4 v = *(const u32x4*)(base + (long)k * INW);
;       float u[8] = {bflo(v[0]), bfhi(v[0]), bflo(v[1]), bfhi(v[1]), bflo(v[2]), bfhi(v[2]), bflo(v[3]), bfhi(v[3])};
;       for (int q = 0; q < 8; ++q) a[q] += u[q];
;       const float ic = 1.f / (float)min(w, s + 1);
;       u32x4 o;
;       o[0] = pack2(a[0] * ic - u[0], a[1] * ic - u[1]); o[1] = pack2(a[2] * ic - u[2], a[3] * ic - u[3]);
;       o[2] = pack2(a[4] * ic - u[4], a[5] * ic - u[5]); o[3] = pack2(a[6] * ic - u[6], a[7] * ic - u[7]);
;       *(u32x4*)(pb + (long)(t0 + k) * 512 + cc * 8) = o;
;       if (s - w + 1 >= 0) {
;         const u32x4 x = *(const u32x4*)(base + (long)(k - w + 1) * INW);
;         a[0] -= bflo(x[0]); a[1] -= bfhi(x[0]); a[2] -= bflo(x[1]); a[3] -= bfhi(x[1]); a[4] -= bflo(x[2]); a[5] -= bfhi(x[2]); a[6] -= bflo(x[3]); a[7] -= bfhi(x[3]);
;       }
	v_lshlrev_b32_e32 v24, 16, v132
	v_and_b32_e32 v25, 0xffff0000, v132
	v_lshlrev_b32_e32 v26, 16, v133
	v_and_b32_e32 v27, 0xffff0000, v133
	v_lshlrev_b32_e32 v28, 16, v134
	v_and_b32_e32 v29, 0xffff0000, v134
	v_lshlrev_b32_e32 v30, 16, v135
	v_and_b32_e32 v31, 0xffff0000, v135
	v_pk_add_f32 v[16:17], v[16:17], v[24:25]
	v_pk_add_f32 v[18:19], v[18:19], v[26:27]
	v_pk_add_f32 v[20:21], v[20:21], v[28:29]
	v_pk_add_f32 v[22:23], v[22:23], v[30:31]
	s_cmp_lt_u32 11, s4
	s_cselect_b32 s11, 0x3dba2e8c, s10
	v_mov_b32_e32 v5, s11
	v_cndmask_b32_e64 v2, v4, v5, s[12:13]
	v_pk_fma_f32 v[8:9], v[2:3], v[16:17], v[24:25] op_sel_hi:[0,1,1] neg_lo:[0,0,1] neg_hi:[0,0,1]
	v_pk_fma_f32 v[10:11], v[2:3], v[18:19], v[26:27] op_sel_hi:[0,1,1] neg_lo:[0,0,1] neg_hi:[0,0,1]
	v_pk_fma_f32 v[12:13], v[2:3], v[20:21], v[28:29] op_sel_hi:[0,1,1] neg_lo:[0,0,1] neg_hi:[0,0,1]
	v_pk_fma_f32 v[14:15], v[2:3], v[22:23], v[30:31] op_sel_hi:[0,1,1] neg_lo:[0,0,1] neg_hi:[0,0,1]
	v_cvt_pk_bf16_f32 v8, v8, v9
	v_cvt_pk_bf16_f32 v9, v10, v11
	v_cvt_pk_bf16_f32 v10, v12, v13
	v_cvt_pk_bf16_f32 v11, v14, v15
	global_store_dwordx4 v7, v[8:11], s[18:19]
	s_add_u32 s18, s18, 0x400
	s_addc_u32 s19, s19, 0
	v_lshlrev_b32_e32 v24, 16, v72
	v_and_b32_e32 v25, 0xffff0000, v72
	v_lshlrev_b32_e32 v26, 16, v73
	v_and_b32_e32 v27, 0xffff0000, v73
	v_lshlrev_b32_e32 v28, 16, v74
	v_and_b32_e32 v29, 0xffff0000, v74
	v_lshlrev_b32_e32 v30, 16, v75
	v_and_b32_e32 v31, 0xffff0000, v75
	v_pk_add_f32 v[16:17], v[16:17], v[24:25] neg_lo:[0,1] neg_hi:[0,1]
	v_pk_add_f32 v[18:19], v[18:19], v[26:27] neg_lo:[0,1] neg_hi:[0,1]
	v_pk_add_f32 v[20:21], v[20:21], v[28:29] neg_lo:[0,1] neg_hi:[0,1]
	v_pk_add_f32 v[22:23], v[22:23], v[30:31] neg_lo:[0,1] neg_hi:[0,1]
	s_waitcnt vmcnt(15)
	v_lshlrev_b32_e32 v24, 16, v136
	v_and_b32_e32 v25, 0xffff0000, v136
	v_lshlrev_b32_e32 v26, 16, v137
	v_and_b32_e32 v27, 0xffff0000, v137
	v_lshlrev_b32_e32 v28, 16, v138
	v_and_b32_e32 v29, 0xffff0000, v138
	v_lshlrev_b32_e32 v30, 16, v139
	v_and_b32_e32 v31, 0xffff0000, v139
	v_pk_add_f32 v[16:17], v[16:17], v[24:25]
	v_pk_add_f32 v[18:19], v[18:19], v[26:27]
	v_pk_add_f32 v[20:21], v[20:21], v[28:29]
	v_pk_add_f32 v[22:23], v[22:23], v[30:31]
	s_cmp_lt_u32 12, s4
	s_cselect_b32 s11, 0x3daaaaab, s10
	v_mov_b32_e32 v5, s11
	v_cndmask_b32_e64 v2, v4, v5, s[12:13]
	v_pk_fma_f32 v[8:9], v[2:3], v[16:17], v[24:25] op_sel_hi:[0,1,1] neg_lo:[0,0,1] neg_hi:[0,0,1]
	v_pk_fma_f32 v[10:11], v[2:3], v[18:19], v[26:27] op_sel_hi:[0,1,1] neg_lo:[0,0,1] neg_hi:[0,0,1]
	v_pk_fma_f32 v[12:13], v[2:3], v[20:21], v[28:29] op_sel_hi:[0,1,1] neg_lo:[0,0,1] neg_hi:[0,0,1]
	v_pk_fma_f32 v[14:15], v[2:3], v[22:23], v[30:31] op_sel_hi:[0,1,1] neg_lo:[0,0,1] neg_hi:[0,0,1]
	v_cvt_pk_bf16_f32 v8, v8, v9
	v_cvt_pk_bf16_f32 v9, v10, v11
	v_cvt_pk_bf16_f32 v10, v12, v13
	v_cvt_pk_bf16_f32 v11, v14, v15
	global_store_dwordx4 v7, v[8:11], s[18:19]
	s_add_u32 s18, s18, 0x400
	s_addc_u32 s19, s19, 0
	v_lshlrev_b32_e32 v24, 16, v76
	v_and_b32_e32 v25, 0xffff0000, v76
	v_lshlrev_b32_e32 v26, 16, v77
	v_and_b32_e32 v27, 0xffff0000, v77
	v_lshlrev_b32_e32 v28, 16, v78
	v_and_b32_e32 v29, 0xffff0000, v78
	v_lshlrev_b32_e32 v30, 16, v79
	v_and_b32_e32 v31, 0xffff0000, v79
	v_pk_add_f32 v[16:17], v[16:17], v[24:25] neg_lo:[0,1] neg_hi:[0,1]
	v_pk_add_f32 v[18:19], v[18:19], v[26:27] neg_lo:[0,1] neg_hi:[0,1]
	v_pk_add_f32 v[20:21], v[20:21], v[28:29] neg_lo:[0,1] neg_hi:[0,1]
	v_pk_add_f32 v[22:23], v[22:23], v[30:31] neg_lo:[0,1] neg_hi:[0,1]
	s_waitcnt vmcnt(15)
	v_lshlrev_b32_e32 v24, 16, v140
	v_and_b32_e32 v25, 0xffff0000, v140
	v_lshlrev_b32_e32 v26, 16, v141
	v_and_b32_e32 v27, 0xffff0000, v141
	v_lshlrev_b32_e32 v28, 16, v142
	v_and_b32_e32 v29, 0xffff0000, v142
	v_lshlrev_b32_e32 v30, 16, v143
	v_and_b32_e32 v31, 0xffff0000, v143
	v_pk_add_f32 v[16:17], v[16:17], v[24:25]
	v_pk_add_f32 v[18:19], v[18:19], v[26:27]
	v_pk_add_f32 v[20:21], v[20:21], v[28:29]
	v_pk_add_f32 v[22:23], v[22:23], v[30:31]
	s_cmp_lt_u32 13, s4
	s_cselect_b32 s11, 0x3d9d89d9, s10
	v_mov_b32_e32 v5, s11
	v_cndmask_b32_e64 v2, v4, v5, s[12:13]
	v_pk_fma_f32 v[8:9], v[2:3], v[16:17], v[24:25] op_sel_hi:[0,1,1] neg_lo:[0,0,1] neg_hi:[0,0,1]
	v_pk_fma_f32 v[10:11], v[2:3], v[18:19], v[26:27] op_sel_hi:[0,1,1] neg_lo:[0,0,1] neg_hi:[0,0,1]
	v_pk_fma_f32 v[12:13], v[2:3], v[20:21], v[28:29] op_sel_hi:[0,1,1] neg_lo:[0,0,1] neg_hi:[0,0,1]
	v_pk_fma_f32 v[14:15], v[2:3], v[22:23], v[30:31] op_sel_hi:[0,1,1] neg_lo:[0,0,1] neg_hi:[0,0,1]
	v_cvt_pk_bf16_f32 v8, v8, v9
	v_cvt_pk_bf16_f32 v9, v10, v11
	v_cvt_pk_bf16_f32 v10, v12, v13
	v_cvt_pk_bf16_f32 v11, v14, v15
	global_store_dwordx4 v7, v[8:11], s[18:19]
	s_add_u32 s18, s18, 0x400
	s_addc_u32 s19, s19, 0
	v_lshlrev_b32_e32 v24, 16, v80
	v_and_b32_e32 v25, 0xffff0000, v80
	v_lshlrev_b32_e32 v26, 16, v81
	v_and_b32_e32 v27, 0xffff0000, v81
	v_lshlrev_b32_e32 v28, 16, v82
	v_and_b32_e32 v29, 0xffff0000, v82
	v_lshlrev_b32_e32 v30, 16, v83
	v_and_b32_e32 v31, 0xffff0000, v83
	v_pk_add_f32 v[16:17], v[16:17], v[24:25] neg_lo:[0,1] neg_hi:[0,1]
	v_pk_add_f32 v[18:19], v[18:19], v[26:27] neg_lo:[0,1] neg_hi:[0,1]
	v_pk_add_f32 v[20:21], v[20:21], v[28:29] neg_lo:[0,1] neg_hi:[0,1]
	v_pk_add_f32 v[22:23], v[22:23], v[30:31] neg_lo:[0,1] neg_hi:[0,1]
	s_waitcnt vmcnt(15)
; DI unsigned pack2(float a, float b) { f2_t v = {a, b}; bf2_t r = __builtin_convertvector(v, bf2_t); return __builtin_bit_cast(unsigned, r); }
; DI float bflo(unsigned v) { return __uint_as_float(v << 16); }
; DI float bfhi(unsigned v) { return __uint_as_float(v & 0xffff0000u); }
; DI void mix_pool(WVP const u16* __restrict__ proj, u16* __restrict__ pb) {
;     ...
;   for (int idx = BID * NTHR + tid; idx < (TOK / 16) * 64; idx += GRD * NTHR) {
;     const int cc = idx & 63, t0 = (idx >> 6) * 16, gi = cc >> 4, w = 2 << gi, s0 = t0 & (SEQ - 1);
;     const u16* base = proj + (long)t0 * INW + cc * 8;
;     float a[8] = {0, 0, 0, 0, 0, 0, 0, 0};
;     for (int i = 1; i < w; ++i) {
;       if (s0 - i >= 0) {
;         const u32x4 v = *(const u32x4*)(base - (long)i * INW);
;         a[0] += bflo(v[0]); a[1] += bfhi(v[0]); a[2] += bflo(v[1]); a[3] += bfhi(v[1]); a[4] += bflo(v[2]); a[5] += bfhi(v[2]); a[6] += bflo(v[3]); a[7] += bfhi(v[3]);
;       }
;     }
; #pragma unroll 4
;     for (int k = 0; k < 16; ++k) {
;       const int s = s0 + k;
;       const u32x4 v = *(const u32x4*)(base + (long)k * INW);
;       float u[8] = {bflo(v[0]), bfhi(v[0]), bflo(v[1]), bfhi(v[1]), bflo(v[2]), bfhi(v[2]), bflo(v[3]), bfhi(v[3])};
;       for (int q = 0; q < 8; ++q) a[q] += u[q];
;       const float ic = 1.f / (float)min(w, s + 1);
;       u32x4 o;
;       o[0] = pack2(a[0] * ic - u[0], a[1] * ic - u[1]); o[1] = pack2(a[2] * ic - u[2], a[3] * ic - u[3]);
;       o[2] = pack2(a[4] * ic - u[4], a[5] * ic - u[5]); o[3] = pack2(a[6] * ic - u[6], a[7] * ic - u[7]);
;       *(u32x4*)(pb + (long)(t0 + k) * 512 + cc * 8) = o;
;       if (s - w + 1 >= 0) {
;         const u32x4 x = *(const u32x4*)(base + (long)(k - w + 1) * INW);
;         a[0] -= bflo(x[0]); a[1] -= bfhi(x[0]); a[2] -= bflo(x[1]); a[3] -= bfhi(x[1]); a[4] -= bflo(x[2]); a[5] -= bfhi(x[2]); a[6] -= bflo(x[3]); a[7] -= bfhi(x[3]);
;       }
;     }
;   }
	v_lshlrev_b32_e32 v24, 16, v144
	v_and_b32_e32 v25, 0xffff0000, v144
	v_lshlrev_b32_e32 v26, 16, v145
	v_and_b32_e32 v27, 0xffff0000, v145
	v_lshlrev_b32_e32 v28, 16, v146
	v_and_b32_e32 v29, 0xffff0000, v146
	v_lshlrev_b32_e32 v30, 16, v147
	v_and_b32_e32 v31, 0xffff0000, v147
	v_pk_add_f32 v[16:17], v[16:17], v[24:25]
	v_pk_add_f32 v[18:19], v[18:19], v[26:27]
	v_pk_add_f32 v[20:21], v[20:21], v[28:29]
	v_pk_add_f32 v[22:23], v[22:23], v[30:31]
	s_cmp_lt_u32 14, s4
	s_cselect_b32 s11, 0x3d924925, s10
	v_mov_b32_e32 v5, s11
	v_cndmask_b32_e64 v2, v4, v5, s[12:13]
	v_pk_fma_f32 v[8:9], v[2:3], v[16:17], v[24:25] op_sel_hi:[0,1,1] neg_lo:[0,0,1] neg_hi:[0,0,1]
	v_pk_fma_f32 v[10:11], v[2:3], v[18:19], v[26:27] op_sel_hi:[0,1,1] neg_lo:[0,0,1] neg_hi:[0,0,1]
	v_pk_fma_f32 v[12:13], v[2:3], v[20:21], v[28:29] op_sel_hi:[0,1,1] neg_lo:[0,0,1] neg_hi:[0,0,1]
	v_pk_fma_f32 v[14:15], v[2:3], v[22:23], v[30:31] op_sel_hi:[0,1,1] neg_lo:[0,0,1] neg_hi:[0,0,1]
	v_cvt_pk_bf16_f32 v8, v8, v9
	v_cvt_pk_bf16_f32 v9, v10, v11
	v_cvt_pk_bf16_f32 v10, v12, v13
	v_cvt_pk_bf16_f32 v11, v14, v15
	global_store_dwordx4 v7, v[8:11], s[18:19]
	s_add_u32 s18, s18, 0x400
	s_addc_u32 s19, s19, 0
	v_lshlrev_b32_e32 v24, 16, v84
	v_and_b32_e32 v25, 0xffff0000, v84
	v_lshlrev_b32_e32 v26, 16, v85
	v_and_b32_e32 v27, 0xffff0000, v85
	v_lshlrev_b32_e32 v28, 16, v86
	v_and_b32_e32 v29, 0xffff0000, v86
	v_lshlrev_b32_e32 v30, 16, v87
	v_and_b32_e32 v31, 0xffff0000, v87
	v_pk_add_f32 v[16:17], v[16:17], v[24:25] neg_lo:[0,1] neg_hi:[0,1]
	v_pk_add_f32 v[18:19], v[18:19], v[26:27] neg_lo:[0,1] neg_hi:[0,1]
	v_pk_add_f32 v[20:21], v[20:21], v[28:29] neg_lo:[0,1] neg_hi:[0,1]
	v_pk_add_f32 v[22:23], v[22:23], v[30:31] neg_lo:[0,1] neg_hi:[0,1]
	s_waitcnt vmcnt(15)
	v_lshlrev_b32_e32 v24, 16, v148
	v_and_b32_e32 v25, 0xffff0000, v148
	v_lshlrev_b32_e32 v26, 16, v149
	v_and_b32_e32 v27, 0xffff0000, v149
	v_lshlrev_b32_e32 v28, 16, v150
	v_and_b32_e32 v29, 0xffff0000, v150
	v_lshlrev_b32_e32 v30, 16, v151
	v_and_b32_e32 v31, 0xffff0000, v151
	v_pk_add_f32 v[16:17], v[16:17], v[24:25]
	v_pk_add_f32 v[18:19], v[18:19], v[26:27]
	v_pk_add_f32 v[20:21], v[20:21], v[28:29]
	v_pk_add_f32 v[22:23], v[22:23], v[30:31]
	s_cmp_lt_u32 15, s4
	s_cselect_b32 s11, 0x3d888889, s10
	v_mov_b32_e32 v5, s11
	v_cndmask_b32_e64 v2, v4, v5, s[12:13]
	v_pk_fma_f32 v[8:9], v[2:3], v[16:17], v[24:25] op_sel_hi:[0,1,1] neg_lo:[0,0,1] neg_hi:[0,0,1]
	v_pk_fma_f32 v[10:11], v[2:3], v[18:19], v[26:27] op_sel_hi:[0,1,1] neg_lo:[0,0,1] neg_hi:[0,0,1]
	v_pk_fma_f32 v[12:13], v[2:3], v[20:21], v[28:29] op_sel_hi:[0,1,1] neg_lo:[0,0,1] neg_hi:[0,0,1]
	v_pk_fma_f32 v[14:15], v[2:3], v[22:23], v[30:31] op_sel_hi:[0,1,1] neg_lo:[0,0,1] neg_hi:[0,0,1]
	v_cvt_pk_bf16_f32 v8, v8, v9
	v_cvt_pk_bf16_f32 v9, v10, v11
	v_cvt_pk_bf16_f32 v10, v12, v13
	v_cvt_pk_bf16_f32 v11, v14, v15
	global_store_dwordx4 v7, v[8:11], s[18:19]
	s_add_u32 s18, s18, 0x400
	s_addc_u32 s19, s19, 0
	v_lshlrev_b32_e32 v24, 16, v88
	v_and_b32_e32 v25, 0xffff0000, v88
	v_lshlrev_b32_e32 v26, 16, v89
	v_and_b32_e32 v27, 0xffff0000, v89
	v_lshlrev_b32_e32 v28, 16, v90
	v_and_b32_e32 v29, 0xffff0000, v90
	v_lshlrev_b32_e32 v30, 16, v91
	v_and_b32_e32 v31, 0xffff0000, v91
	v_pk_add_f32 v[16:17], v[16:17], v[24:25] neg_lo:[0,1] neg_hi:[0,1]
	v_pk_add_f32 v[18:19], v[18:19], v[26:27] neg_lo:[0,1] neg_hi:[0,1]
	v_pk_add_f32 v[20:21], v[20:21], v[28:29] neg_lo:[0,1] neg_hi:[0,1]
	v_pk_add_f32 v[22:23], v[22:23], v[30:31] neg_lo:[0,1] neg_hi:[0,1]
	s_waitcnt vmcnt(15)
	v_lshlrev_b32_e32 v24, 16, v152
	v_and_b32_e32 v25, 0xffff0000, v152
	v_lshlrev_b32_e32 v26, 16, v153
	v_and_b32_e32 v27, 0xffff0000, v153
	v_lshlrev_b32_e32 v28, 16, v154
	v_and_b32_e32 v29, 0xffff0000, v154
	v_lshlrev_b32_e32 v30, 16, v155
	v_and_b32_e32 v31, 0xffff0000, v155
	v_pk_add_f32 v[16:17], v[16:17], v[24:25]
	v_pk_add_f32 v[18:19], v[18:19], v[26:27]
	v_pk_add_f32 v[20:21], v[20:21], v[28:29]
	v_pk_add_f32 v[22:23], v[22:23], v[30:31]
	v_mov_b32_e32 v2, v4
	v_pk_fma_f32 v[8:9], v[2:3], v[16:17], v[24:25] op_sel_hi:[0,1,1] neg_lo:[0,0,1] neg_hi:[0,0,1]
	v_pk_fma_f32 v[10:11], v[2:3], v[18:19], v[26:27] op_sel_hi:[0,1,1] neg_lo:[0,0,1] neg_hi:[0,0,1]
	v_pk_fma_f32 v[12:13], v[2:3], v[20:21], v[28:29] op_sel_hi:[0,1,1] neg_lo:[0,0,1] neg_hi:[0,0,1]
	v_pk_fma_f32 v[14:15], v[2:3], v[22:23], v[30:31] op_sel_hi:[0,1,1] neg_lo:[0,0,1] neg_hi:[0,0,1]
	v_cvt_pk_bf16_f32 v8, v8, v9
	v_cvt_pk_bf16_f32 v9, v10, v11
	v_cvt_pk_bf16_f32 v10, v12, v13
	v_cvt_pk_bf16_f32 v11, v14, v15
	global_store_dwordx4 v7, v[8:11], s[18:19]
	s_lshl_b32 s11, s53, 3
	s_add_i32 s0, s0, s11
	s_cmpk_lt_u32 s0, 0x800
	s_cbranch_scc1 .Lmp_item
.Lmp_done:
	s_mov_b64 exec, -1
